# prompt pool units: output tile transposed through wave-private LDS so each store instruction writes 4 full 256-byte rows
# speedup vs baseline: 1.0034x; 1.0034x over previous
.LBB0_555:
	s_waitcnt vmcnt(0)
	v_and_b32_e32 v212, 63, v204
	v_lshrrev_b32_e32 v213, 4, v212
	v_and_b32_e32 v212, 15, v212
	v_lshlrev_b32_e32 v213, 2, v213
	v_lshl_or_b32 v212, v212, 4, v213
	ds_bpermute_b32 v2, v212, v2
	ds_bpermute_b32 v3, v212, v3
	ds_bpermute_b32 v4, v212, v4
	ds_bpermute_b32 v5, v212, v5
	ds_bpermute_b32 v6, v212, v6
	ds_bpermute_b32 v7, v212, v7
	ds_bpermute_b32 v8, v212, v8
	ds_bpermute_b32 v9, v212, v9
	ds_bpermute_b32 v10, v212, v10
	ds_bpermute_b32 v11, v212, v11
	ds_bpermute_b32 v12, v212, v12
	ds_bpermute_b32 v13, v212, v13
	ds_bpermute_b32 v14, v212, v14
	ds_bpermute_b32 v15, v212, v15
	ds_bpermute_b32 v16, v212, v16
	ds_bpermute_b32 v17, v212, v17
	s_waitcnt lgkmcnt(0)
	ds_bpermute_b32 v18, v212, v18
	ds_bpermute_b32 v19, v212, v19
	ds_bpermute_b32 v20, v212, v20
	ds_bpermute_b32 v21, v212, v21
	ds_bpermute_b32 v22, v212, v22
	ds_bpermute_b32 v23, v212, v23
	ds_bpermute_b32 v24, v212, v24
	ds_bpermute_b32 v25, v212, v25
	ds_bpermute_b32 v26, v212, v26
	ds_bpermute_b32 v27, v212, v27
	ds_bpermute_b32 v28, v212, v28
	ds_bpermute_b32 v29, v212, v29
	ds_bpermute_b32 v30, v212, v30
	ds_bpermute_b32 v31, v212, v31
	ds_bpermute_b32 v32, v212, v32
	ds_bpermute_b32 v33, v212, v33
	s_waitcnt lgkmcnt(0)
	ds_bpermute_b32 v34, v212, v34
	ds_bpermute_b32 v35, v212, v35
	ds_bpermute_b32 v36, v212, v36
	ds_bpermute_b32 v37, v212, v37
	ds_bpermute_b32 v38, v212, v38
	ds_bpermute_b32 v39, v212, v39
	ds_bpermute_b32 v40, v212, v40
	ds_bpermute_b32 v41, v212, v41
	ds_bpermute_b32 v42, v212, v42
	ds_bpermute_b32 v43, v212, v43
	ds_bpermute_b32 v44, v212, v44
	ds_bpermute_b32 v45, v212, v45
	ds_bpermute_b32 v46, v212, v46
	ds_bpermute_b32 v47, v212, v47
	ds_bpermute_b32 v48, v212, v48
	ds_bpermute_b32 v49, v212, v49
	s_waitcnt lgkmcnt(0)
	ds_bpermute_b32 v50, v212, v50
	ds_bpermute_b32 v51, v212, v51
	ds_bpermute_b32 v52, v212, v52
	ds_bpermute_b32 v53, v212, v53
	ds_bpermute_b32 v54, v212, v54
	ds_bpermute_b32 v55, v212, v55
	ds_bpermute_b32 v56, v212, v56
	ds_bpermute_b32 v57, v212, v57
	ds_bpermute_b32 v58, v212, v58
	ds_bpermute_b32 v59, v212, v59
	ds_bpermute_b32 v60, v212, v60
	ds_bpermute_b32 v61, v212, v61
	ds_bpermute_b32 v62, v212, v62
	ds_bpermute_b32 v63, v212, v63
	ds_bpermute_b32 v64, v212, v64
	ds_bpermute_b32 v65, v212, v65
	s_waitcnt lgkmcnt(0)
	ds_bpermute_b32 v66, v212, v66
	ds_bpermute_b32 v67, v212, v67
	ds_bpermute_b32 v68, v212, v68
	ds_bpermute_b32 v69, v212, v69
	ds_bpermute_b32 v70, v212, v70
	ds_bpermute_b32 v71, v212, v71
	ds_bpermute_b32 v72, v212, v72
	ds_bpermute_b32 v73, v212, v73
	ds_bpermute_b32 v74, v212, v74
	ds_bpermute_b32 v75, v212, v75
	ds_bpermute_b32 v76, v212, v76
	ds_bpermute_b32 v77, v212, v77
	ds_bpermute_b32 v78, v212, v78
	ds_bpermute_b32 v79, v212, v79
	ds_bpermute_b32 v80, v212, v80
	ds_bpermute_b32 v81, v212, v81
	s_waitcnt lgkmcnt(0)
	ds_bpermute_b32 v82, v212, v82
	ds_bpermute_b32 v83, v212, v83
	ds_bpermute_b32 v84, v212, v84
	ds_bpermute_b32 v85, v212, v85
	ds_bpermute_b32 v86, v212, v86
	ds_bpermute_b32 v87, v212, v87
	ds_bpermute_b32 v88, v212, v88
	ds_bpermute_b32 v89, v212, v89
	ds_bpermute_b32 v90, v212, v90
	ds_bpermute_b32 v91, v212, v91
	ds_bpermute_b32 v92, v212, v92
	ds_bpermute_b32 v93, v212, v93
	ds_bpermute_b32 v94, v212, v94
	ds_bpermute_b32 v95, v212, v95
	ds_bpermute_b32 v96, v212, v96
	ds_bpermute_b32 v97, v212, v97
	s_waitcnt lgkmcnt(0)
	ds_bpermute_b32 v98, v212, v98
	ds_bpermute_b32 v99, v212, v99
	ds_bpermute_b32 v100, v212, v100
	ds_bpermute_b32 v101, v212, v101
	ds_bpermute_b32 v102, v212, v102
	ds_bpermute_b32 v103, v212, v103
	ds_bpermute_b32 v104, v212, v104
	ds_bpermute_b32 v105, v212, v105
	ds_bpermute_b32 v106, v212, v106
	ds_bpermute_b32 v107, v212, v107
	ds_bpermute_b32 v108, v212, v108
	ds_bpermute_b32 v109, v212, v109
	ds_bpermute_b32 v110, v212, v110
	ds_bpermute_b32 v111, v212, v111
	ds_bpermute_b32 v112, v212, v112
	ds_bpermute_b32 v113, v212, v113
	s_waitcnt lgkmcnt(0)
	ds_bpermute_b32 v114, v212, v114
	ds_bpermute_b32 v115, v212, v115
	ds_bpermute_b32 v116, v212, v116
	ds_bpermute_b32 v117, v212, v117
	ds_bpermute_b32 v118, v212, v118
	ds_bpermute_b32 v119, v212, v119
	ds_bpermute_b32 v120, v212, v120
	ds_bpermute_b32 v121, v212, v121
	ds_bpermute_b32 v122, v212, v122
	ds_bpermute_b32 v123, v212, v123
	ds_bpermute_b32 v124, v212, v124
	ds_bpermute_b32 v125, v212, v125
	ds_bpermute_b32 v126, v212, v126
	ds_bpermute_b32 v127, v212, v127
	ds_bpermute_b32 v128, v212, v128
	ds_bpermute_b32 v129, v212, v129
	s_waitcnt lgkmcnt(0)
	s_add_i32 s0, s19, s22
	v_add3_u32 v0, s0, 1, v176
	v_min_i32_e32 v0, s24, v0
	v_cvt_f32_i32_e32 v0, v0
	s_lshl_b32 s72, s23, 1
	v_div_scale_f32 v212, s[0:1], v0, v0, 1.0
	v_rcp_f32_e32 v213, v212
	v_div_scale_f32 v214, vcc, 1.0, v0, 1.0
	v_fma_f32 v215, -v212, v213, 1.0
	v_fmac_f32_e32 v213, v215, v213
	v_mul_f32_e32 v215, v214, v213
	v_fma_f32 v222, -v212, v215, v214
	v_fmac_f32_e32 v215, v222, v213
	v_fma_f32 v212, -v212, v215, v214
	v_div_fmas_f32 v212, v212, v213, v215
	v_div_fixup_f32 v0, v212, v0, 1.0
	v_pk_fma_f32 v[138:139], v[0:1], v[144:145], v[138:139] op_sel_hi:[0,1,1] neg_lo:[0,0,1] neg_hi:[0,0,1]
	v_pk_fma_f32 v[136:137], v[0:1], v[142:143], v[136:137] op_sel_hi:[0,1,1] neg_lo:[0,0,1] neg_hi:[0,0,1]
	v_pk_fma_f32 v[134:135], v[0:1], v[140:141], v[134:135] op_sel_hi:[0,1,1] neg_lo:[0,0,1] neg_hi:[0,0,1]
	v_pk_fma_f32 v[130:131], v[0:1], v[132:133], v[130:131] op_sel_hi:[0,1,1] neg_lo:[0,0,1] neg_hi:[0,0,1]
	v_cvt_pk_bf16_f32 v138, v138, v139
	v_cvt_pk_bf16_f32 v139, v136, v137
	v_cvt_pk_bf16_f32 v140, v134, v135
	v_cvt_pk_bf16_f32 v141, v130, v131
	v_pk_fma_f32 v[154:155], v[0:1], v[160:161], v[154:155] op_sel_hi:[0,1,1] neg_lo:[0,0,1] neg_hi:[0,0,1]
	v_pk_fma_f32 v[152:153], v[0:1], v[158:159], v[152:153] op_sel_hi:[0,1,1] neg_lo:[0,0,1] neg_hi:[0,0,1]
	v_mfma_f32_16x16x32_bf16 v[94:97], v[94:97], v[138:141], 0
	v_fma_f32 v150, v0, v156, -v150
	v_fma_f32 v151, v0, v157, -v151
	v_pk_fma_f32 v[146:147], v[0:1], v[146:147], v[148:149] op_sel_hi:[0,1,1] neg_lo:[0,0,1] neg_hi:[0,0,1]
	v_cvt_pk_bf16_f32 v154, v154, v155
	v_mfma_f32_16x16x32_bf16 v[38:41], v[38:41], v[138:141], 0
	v_cvt_pk_bf16_f32 v155, v152, v153
	v_cvt_pk_bf16_f32 v156, v150, v151
	v_cvt_pk_bf16_f32 v157, v146, v147
	v_pk_fma_f32 v[170:171], v[0:1], v[186:187], v[170:171] op_sel_hi:[0,1,1] neg_lo:[0,0,1] neg_hi:[0,0,1]
	v_pk_fma_f32 v[174:175], v[0:1], v[174:175], v[168:169] op_sel_hi:[0,1,1] neg_lo:[0,0,1] neg_hi:[0,0,1]
	v_mfma_f32_16x16x32_bf16 v[78:81], v[78:81], v[154:157], v[94:97]
	v_fma_f32 v166, v0, v172, -v166
	v_fma_f32 v167, v0, v173, -v167
	v_pk_fma_f32 v[162:163], v[0:1], v[162:163], v[164:165] op_sel_hi:[0,1,1] neg_lo:[0,0,1] neg_hi:[0,0,1]
	v_cvt_pk_bf16_f32 v168, v170, v171
	v_mfma_f32_16x16x32_bf16 v[38:41], v[42:45], v[154:157], v[38:41]
	v_cvt_pk_bf16_f32 v169, v174, v175
	v_cvt_pk_bf16_f32 v170, v166, v167
	v_cvt_pk_bf16_f32 v171, v162, v163
	v_pk_fma_f32 v[130:131], v[0:1], v[202:203], v[188:189] op_sel_hi:[0,1,1] neg_lo:[0,0,1] neg_hi:[0,0,1]
	v_pk_fma_f32 v[94:95], v[0:1], v[200:201], v[192:193] op_sel_hi:[0,1,1] neg_lo:[0,0,1] neg_hi:[0,0,1]
	v_mfma_f32_16x16x32_bf16 v[66:69], v[66:69], v[168:171], v[78:81]
	v_cvt_pk_bf16_f32 v130, v130, v131
	v_cvt_pk_bf16_f32 v131, v94, v95
	v_pk_fma_f32 v[94:95], v[0:1], v[198:199], v[194:195] op_sel_hi:[0,1,1] neg_lo:[0,0,1] neg_hi:[0,0,1]
	v_mfma_f32_16x16x32_bf16 v[38:41], v[46:49], v[168:171], v[38:41]
	v_fma_f32 v78, v0, v190, -v196
	v_fma_f32 v79, v0, v191, -v197
	v_cvt_pk_bf16_f32 v132, v94, v95
	v_cvt_pk_bf16_f32 v133, v78, v79
	v_mfma_f32_16x16x32_bf16 v[42:45], v[102:105], v[138:141], 0
	v_or_b32_e32 v0, s21, v176
	v_mfma_f32_16x16x32_bf16 v[34:37], v[34:37], v[130:133], v[66:69]
	v_mfma_f32_16x16x32_bf16 v[66:69], v[126:129], v[138:141], 0
	v_mfma_f32_16x16x32_bf16 v[38:41], v[50:53], v[130:133], v[38:41]
	s_nop 5
	v_cvt_pk_bf16_f32 v34, v34, v35
	v_cvt_pk_bf16_f32 v35, v36, v37
	v_mfma_f32_16x16x32_bf16 v[46:49], v[54:57], v[138:141], 0
	v_add_u32_e32 v54, s19, v0
	v_ashrrev_i32_e32 v55, 31, v54
	v_lshlrev_b64 v[54:55], 11, v[54:55]
	v_mfma_f32_16x16x32_bf16 v[50:53], v[106:109], v[138:141], 0
	v_lshl_add_u64 v[54:55], s[76:77], 0, v[54:55]
	v_lshl_add_u64 v[54:55], v[54:55], 0, s[72:73]
	v_lshlrev_b32_e32 v0, 3, v225
	v_mfma_f32_16x16x32_bf16 v[30:33], v[30:33], v[138:141], 0
	v_lshl_add_u64 v[54:55], v[54:55], 0, v[0:1]
	s_mul_i32 s100, s19, 0x110
	s_add_i32 s100, s100, 0x10000
	v_mov_b32_e32 v213, 0x110
	v_mul_u32_u24_e32 v212, v176, v213
	v_lshl_add_u32 v212, v225, 3, v212
	v_add_u32_e32 v212, s100, v212
	v_mul_u32_u24_e32 v213, v225, v213
	v_lshl_add_u32 v213, v176, 4, v213
	v_add_u32_e32 v213, s100, v213
	ds_write_b64 v212, v[34:35]
	v_mfma_f32_16x16x32_bf16 v[14:17], v[14:17], v[138:141], 0
	v_mfma_f32_16x16x32_bf16 v[42:45], v[82:85], v[154:157], v[42:45]
	v_mfma_f32_16x16x32_bf16 v[66:69], v[70:73], v[154:157], v[66:69]
	v_mfma_f32_16x16x32_bf16 v[46:49], v[58:61], v[154:157], v[46:49]
	v_mfma_f32_16x16x32_bf16 v[50:53], v[110:113], v[154:157], v[50:53]
	v_mfma_f32_16x16x32_bf16 v[26:29], v[26:29], v[154:157], v[30:33]
	v_mfma_f32_16x16x32_bf16 v[10:13], v[10:13], v[154:157], v[14:17]
	v_mfma_f32_16x16x32_bf16 v[42:45], v[86:89], v[168:171], v[42:45]
	v_mfma_f32_16x16x32_bf16 v[66:69], v[74:77], v[168:171], v[66:69]
	v_mfma_f32_16x16x32_bf16 v[46:49], v[62:65], v[168:171], v[46:49]
	v_mfma_f32_16x16x32_bf16 v[50:53], v[98:101], v[168:171], v[50:53]
	v_mfma_f32_16x16x32_bf16 v[22:25], v[22:25], v[168:171], v[26:29]
	v_mfma_f32_16x16x32_bf16 v[6:9], v[6:9], v[168:171], v[10:13]
	s_nop 1
	v_cvt_pk_bf16_f32 v26, v38, v39
	v_cvt_pk_bf16_f32 v27, v40, v41
	ds_write_b64 v212, v[26:27] offset:64
	v_mfma_f32_16x16x32_bf16 v[42:45], v[90:93], v[130:133], v[42:45]
	v_mfma_f32_16x16x32_bf16 v[66:69], v[122:125], v[130:133], v[66:69]
	v_mfma_f32_16x16x32_bf16 v[46:49], v[114:117], v[130:133], v[46:49]
	v_mfma_f32_16x16x32_bf16 v[50:53], v[118:121], v[130:133], v[50:53]
	s_nop 5
	v_cvt_pk_bf16_f32 v30, v66, v67
	v_cvt_pk_bf16_f32 v31, v68, v69
	ds_write_b64 v212, v[30:31] offset:32
	v_mfma_f32_16x16x32_bf16 v[18:21], v[18:21], v[130:133], v[22:25]
	v_mfma_f32_16x16x32_bf16 v[2:5], v[2:5], v[130:133], v[6:9]
	s_nop 1
	v_cvt_pk_bf16_f32 v22, v42, v43
	v_cvt_pk_bf16_f32 v23, v44, v45
	ds_write_b64 v212, v[22:23] offset:96
	v_cvt_pk_bf16_f32 v22, v46, v47
	v_cvt_pk_bf16_f32 v23, v48, v49
	v_cvt_pk_bf16_f32 v14, v50, v51
	v_cvt_pk_bf16_f32 v15, v52, v53
	v_cvt_pk_bf16_f32 v10, v18, v19
	v_cvt_pk_bf16_f32 v11, v20, v21
	v_cvt_pk_bf16_f32 v2, v2, v3
	v_cvt_pk_bf16_f32 v3, v4, v5
	ds_write_b64 v212, v[22:23] offset:128
	ds_write_b64 v212, v[14:15] offset:160
	ds_write_b64 v212, v[10:11] offset:192
	ds_write_b64 v212, v[2:3] offset:224
	s_waitcnt lgkmcnt(0)
	v_sub_u32_e32 v214, v225, v176
	v_lshlrev_b32_e32 v214, 11, v214
	v_lshl_add_u32 v214, v176, 4, v214
	v_lshlrev_b32_e32 v215, 3, v225
	v_sub_u32_e32 v214, v214, v215
	v_ashrrev_i32_e32 v215, 31, v214
	v_lshl_add_u64 v[54:55], v[54:55], 0, v[214:215]
	s_mov_b32 s100, 0x2000
	s_mov_b32 s101, 0
	ds_read_b128 v[2:5], v213
	ds_read_b128 v[6:9], v213 offset:1088
	ds_read_b128 v[10:13], v213 offset:2176
	ds_read_b128 v[14:17], v213 offset:3264
	s_waitcnt lgkmcnt(3)
	global_store_dwordx4 v[54:55], v[2:5], off
	v_lshl_add_u64 v[54:55], v[54:55], 0, s[100:101]
	s_waitcnt lgkmcnt(2)
	global_store_dwordx4 v[54:55], v[6:9], off
	v_lshl_add_u64 v[54:55], v[54:55], 0, s[100:101]
	s_waitcnt lgkmcnt(1)
	global_store_dwordx4 v[54:55], v[10:13], off
	v_lshl_add_u64 v[54:55], v[54:55], 0, s[100:101]
	s_waitcnt lgkmcnt(0)
	global_store_dwordx4 v[54:55], v[14:17], off
